# PRO adaLN GEMV inner loop hand-written (LDS reads batched per k-group, plain FMAs)
# baseline (speedup 1.0000x reference)
.LBB0_70:
	s_add_u32 s26, s0, 0xfffc0080
	s_addc_u32 s27, s1, -1
	s_cmp_eq_u32 s35, 12
	s_cselect_b32 s31, s67, s27
	s_cselect_b32 s30, s66, s26
	s_cselect_b32 s27, s23, s34
	s_cselect_b32 s26, s28, s33
	s_add_i32 s40, 0, 0x10000
	s_add_i32 s42, 0, 0x14000
	v_add_u32_e32 v138, s40, v186
	v_add_u32_e32 v158, s42, v186
	ds_read_b128 v[122:125], v138
	ds_read_b128 v[130:133], v138 offset:1024
	ds_read_b128 v[134:137], v138 offset:2048
	ds_read_b128 v[138:141], v138 offset:3072
	ds_read_b128 v[142:145], v158
	ds_read_b128 v[150:153], v158 offset:1024
	ds_read_b128 v[154:157], v158 offset:2048
	ds_read_b128 v[158:161], v158 offset:3072
	s_add_i32 m0, s77, 0xc000
	ds_read_b128 v[172:175], v188
	ds_read_b128 v[190:193], v188 offset:1024
	ds_read_b128 v[194:197], v188 offset:2048
	ds_read_b128 v[198:201], v188 offset:3072
	ds_read_b128 v[218:221], v188 offset:4096
	ds_read_b128 v[222:225], v188 offset:5120
	ds_read_b128 v[226:229], v188 offset:6144
	ds_read_b128 v[230:233], v188 offset:7168
	global_load_lds_dwordx4 v168, s[0:1]
	s_add_i32 m0, s77, 0xe000
	s_nop 0
	global_load_lds_dwordx4 v170, s[0:1]
	s_waitcnt vmcnt(8)
	s_waitcnt lgkmcnt(0)
	s_barrier
	s_setprio 1
	s_waitcnt lgkmcnt(0)
	v_mfma_f32_16x16x32_bf16 v[126:129], v[122:125], v[172:175], v[126:129]
	v_mfma_f32_16x16x32_bf16 v[62:65], v[134:137], v[172:175], v[62:65]
	v_mfma_f32_16x16x32_bf16 v[118:121], v[122:125], v[194:197], v[118:121]
	v_mfma_f32_16x16x32_bf16 v[54:57], v[134:137], v[194:197], v[54:57]
	v_mfma_f32_16x16x32_bf16 v[110:113], v[122:125], v[218:221], v[110:113]
	v_mfma_f32_16x16x32_bf16 v[46:49], v[134:137], v[218:221], v[46:49]
	v_mfma_f32_16x16x32_bf16 v[102:105], v[122:125], v[226:229], v[102:105]
	v_mfma_f32_16x16x32_bf16 v[38:41], v[134:137], v[226:229], v[38:41]
	v_mfma_f32_16x16x32_bf16 v[126:129], v[130:133], v[190:193], v[126:129]
	v_mfma_f32_16x16x32_bf16 v[62:65], v[138:141], v[190:193], v[62:65]
	v_mfma_f32_16x16x32_bf16 v[118:121], v[130:133], v[198:201], v[118:121]
	v_mfma_f32_16x16x32_bf16 v[54:57], v[138:141], v[198:201], v[54:57]
	v_mfma_f32_16x16x32_bf16 v[110:113], v[130:133], v[222:225], v[110:113]
	v_mfma_f32_16x16x32_bf16 v[46:49], v[138:141], v[222:225], v[46:49]
	v_mfma_f32_16x16x32_bf16 v[102:105], v[130:133], v[230:233], v[102:105]
	v_mfma_f32_16x16x32_bf16 v[38:41], v[138:141], v[230:233], v[38:41]
	s_setprio 0
	s_setprio 1
	v_mfma_f32_16x16x32_bf16 v[146:149], v[142:145], v[172:175], v[146:149]
	v_mfma_f32_16x16x32_bf16 v[58:61], v[154:157], v[172:175], v[58:61]
	v_mfma_f32_16x16x32_bf16 v[114:117], v[142:145], v[194:197], v[114:117]
	v_mfma_f32_16x16x32_bf16 v[50:53], v[154:157], v[194:197], v[50:53]
	v_mfma_f32_16x16x32_bf16 v[106:109], v[142:145], v[218:221], v[106:109]
	v_mfma_f32_16x16x32_bf16 v[42:45], v[154:157], v[218:221], v[42:45]
	v_mfma_f32_16x16x32_bf16 v[98:101], v[142:145], v[226:229], v[98:101]
	v_mfma_f32_16x16x32_bf16 v[34:37], v[154:157], v[226:229], v[34:37]
	v_mfma_f32_16x16x32_bf16 v[146:149], v[150:153], v[190:193], v[146:149]
	v_mfma_f32_16x16x32_bf16 v[58:61], v[158:161], v[190:193], v[58:61]
	v_mfma_f32_16x16x32_bf16 v[114:117], v[150:153], v[198:201], v[114:117]
	v_mfma_f32_16x16x32_bf16 v[50:53], v[158:161], v[198:201], v[50:53]
	v_mfma_f32_16x16x32_bf16 v[106:109], v[150:153], v[222:225], v[106:109]
	v_mfma_f32_16x16x32_bf16 v[42:45], v[158:161], v[222:225], v[42:45]
	v_mfma_f32_16x16x32_bf16 v[98:101], v[150:153], v[230:233], v[98:101]
	v_mfma_f32_16x16x32_bf16 v[34:37], v[158:161], v[230:233], v[34:37]
	s_setprio 0
	s_barrier
	s_add_i32 s40, s40, s76
	s_mov_b32 m0, s40
	ds_read_b128 v[172:175], v188 offset:16384
	ds_read_b128 v[190:193], v188 offset:17408
	ds_read_b128 v[194:197], v188 offset:18432
	ds_read_b128 v[198:201], v188 offset:19456
	ds_read_b128 v[218:221], v188 offset:20480
	ds_read_b128 v[222:225], v188 offset:21504
	ds_read_b128 v[226:229], v188 offset:22528
	ds_read_b128 v[230:233], v188 offset:23552
	global_load_lds_dwordx4 v0, s[26:27]
	s_add_i32 m0, s40, 0x2000
	s_add_u32 s40, s26, 0x40000
	s_addc_u32 s41, s27, 0
	s_add_u32 s100, s30, s4
	s_addc_u32 s101, s31, s5
	s_add_i32 s42, s42, s76
	global_load_lds_dwordx4 v166, s[26:27]
	s_mov_b32 m0, s42
	s_nop 0
	global_load_lds_dwordx4 v0, s[40:41]
	s_add_i32 m0, s42, 0x2000
	s_nop 0
	global_load_lds_dwordx4 v166, s[40:41]
	s_mov_b32 m0, s77
	s_nop 0
	global_load_lds_dwordx4 v162, s[30:31]
	s_mov_b32 m0, s80
	s_nop 0
	global_load_lds_dwordx4 v164, s[30:31]
	s_waitcnt vmcnt(8)
	s_waitcnt lgkmcnt(0)
	s_barrier
	s_setprio 1
	s_waitcnt lgkmcnt(0)
	v_mfma_f32_16x16x32_bf16 v[94:97], v[122:125], v[172:175], v[94:97]
	v_mfma_f32_16x16x32_bf16 v[30:33], v[134:137], v[172:175], v[30:33]
	v_mfma_f32_16x16x32_bf16 v[86:89], v[122:125], v[194:197], v[86:89]
	v_mfma_f32_16x16x32_bf16 v[22:25], v[134:137], v[194:197], v[22:25]
	v_mfma_f32_16x16x32_bf16 v[78:81], v[122:125], v[218:221], v[78:81]
	v_mfma_f32_16x16x32_bf16 v[14:17], v[134:137], v[218:221], v[14:17]
	v_mfma_f32_16x16x32_bf16 v[70:73], v[122:125], v[226:229], v[70:73]
	v_mfma_f32_16x16x32_bf16 v[6:9], v[134:137], v[226:229], v[6:9]
	v_mfma_f32_16x16x32_bf16 v[94:97], v[130:133], v[190:193], v[94:97]
	v_mfma_f32_16x16x32_bf16 v[30:33], v[138:141], v[190:193], v[30:33]
	v_mfma_f32_16x16x32_bf16 v[86:89], v[130:133], v[198:201], v[86:89]
	v_mfma_f32_16x16x32_bf16 v[22:25], v[138:141], v[198:201], v[22:25]
	v_mfma_f32_16x16x32_bf16 v[78:81], v[130:133], v[222:225], v[78:81]
	v_mfma_f32_16x16x32_bf16 v[14:17], v[138:141], v[222:225], v[14:17]
	v_mfma_f32_16x16x32_bf16 v[70:73], v[130:133], v[230:233], v[70:73]
	v_mfma_f32_16x16x32_bf16 v[6:9], v[138:141], v[230:233], v[6:9]
	s_setprio 0
	s_setprio 1
	v_mfma_f32_16x16x32_bf16 v[90:93], v[142:145], v[172:175], v[90:93]
	v_mfma_f32_16x16x32_bf16 v[26:29], v[154:157], v[172:175], v[26:29]
	v_mfma_f32_16x16x32_bf16 v[82:85], v[142:145], v[194:197], v[82:85]
	v_mfma_f32_16x16x32_bf16 v[18:21], v[154:157], v[194:197], v[18:21]
	v_mfma_f32_16x16x32_bf16 v[74:77], v[142:145], v[218:221], v[74:77]
	v_mfma_f32_16x16x32_bf16 v[10:13], v[154:157], v[218:221], v[10:13]
	v_mfma_f32_16x16x32_bf16 v[66:69], v[142:145], v[226:229], v[66:69]
	v_mfma_f32_16x16x32_bf16 v[2:5], v[154:157], v[226:229], v[2:5]
	v_mfma_f32_16x16x32_bf16 v[90:93], v[150:153], v[190:193], v[90:93]
	v_mfma_f32_16x16x32_bf16 v[26:29], v[158:161], v[190:193], v[26:29]
	v_mfma_f32_16x16x32_bf16 v[82:85], v[150:153], v[198:201], v[82:85]
	v_mfma_f32_16x16x32_bf16 v[18:21], v[158:161], v[198:201], v[18:21]
	v_mfma_f32_16x16x32_bf16 v[74:77], v[150:153], v[222:225], v[74:77]
	v_mfma_f32_16x16x32_bf16 v[10:13], v[158:161], v[222:225], v[10:13]
	v_mfma_f32_16x16x32_bf16 v[66:69], v[150:153], v[230:233], v[66:69]
	v_mfma_f32_16x16x32_bf16 v[2:5], v[158:161], v[230:233], v[2:5]
	s_setprio 0
	s_barrier
	s_add_i32 s40, 0, 0x18000
	s_add_i32 s41, 0, 0x1c000
	v_add_u32_e32 v138, s40, v186
	v_add_u32_e32 v158, s41, v186
	ds_read_b128 v[122:125], v138
	ds_read_b128 v[130:133], v138 offset:1024
	ds_read_b128 v[134:137], v138 offset:2048
	ds_read_b128 v[138:141], v138 offset:3072
	ds_read_b128 v[142:145], v158
	ds_read_b128 v[150:153], v158 offset:1024
	ds_read_b128 v[154:157], v158 offset:2048
	ds_read_b128 v[158:161], v158 offset:3072
	s_add_u32 s30, s30, 0x40000
	s_addc_u32 s31, s31, 0
	s_mov_b32 m0, s81
	ds_read_b128 v[172:175], v188 offset:32768
	ds_read_b128 v[190:193], v188 offset:33792
	ds_read_b128 v[194:197], v188 offset:34816
	ds_read_b128 v[198:201], v188 offset:35840
	ds_read_b128 v[218:221], v188 offset:36864
	ds_read_b128 v[222:225], v188 offset:37888
	ds_read_b128 v[226:229], v188 offset:38912
	ds_read_b128 v[230:233], v188 offset:39936
	global_load_lds_dwordx4 v162, s[30:31]
	s_mov_b32 m0, s84
	s_nop 0
	global_load_lds_dwordx4 v164, s[30:31]
	s_waitcnt vmcnt(8)
	s_waitcnt lgkmcnt(0)
	s_barrier
	s_setprio 1
	s_waitcnt lgkmcnt(0)
	v_mfma_f32_16x16x32_bf16 v[126:129], v[122:125], v[172:175], v[126:129]
	v_mfma_f32_16x16x32_bf16 v[62:65], v[134:137], v[172:175], v[62:65]
	v_mfma_f32_16x16x32_bf16 v[118:121], v[122:125], v[194:197], v[118:121]
	v_mfma_f32_16x16x32_bf16 v[54:57], v[134:137], v[194:197], v[54:57]
	v_mfma_f32_16x16x32_bf16 v[110:113], v[122:125], v[218:221], v[110:113]
	v_mfma_f32_16x16x32_bf16 v[46:49], v[134:137], v[218:221], v[46:49]
	v_mfma_f32_16x16x32_bf16 v[102:105], v[122:125], v[226:229], v[102:105]
	v_mfma_f32_16x16x32_bf16 v[38:41], v[134:137], v[226:229], v[38:41]
	v_mfma_f32_16x16x32_bf16 v[126:129], v[130:133], v[190:193], v[126:129]
	v_mfma_f32_16x16x32_bf16 v[62:65], v[138:141], v[190:193], v[62:65]
	v_mfma_f32_16x16x32_bf16 v[118:121], v[130:133], v[198:201], v[118:121]
	v_mfma_f32_16x16x32_bf16 v[54:57], v[138:141], v[198:201], v[54:57]
	v_mfma_f32_16x16x32_bf16 v[110:113], v[130:133], v[222:225], v[110:113]
	v_mfma_f32_16x16x32_bf16 v[46:49], v[138:141], v[222:225], v[46:49]
	v_mfma_f32_16x16x32_bf16 v[102:105], v[130:133], v[230:233], v[102:105]
	v_mfma_f32_16x16x32_bf16 v[38:41], v[138:141], v[230:233], v[38:41]
	s_setprio 0
	s_setprio 1
	v_mfma_f32_16x16x32_bf16 v[146:149], v[142:145], v[172:175], v[146:149]
	v_mfma_f32_16x16x32_bf16 v[58:61], v[154:157], v[172:175], v[58:61]
	v_mfma_f32_16x16x32_bf16 v[114:117], v[142:145], v[194:197], v[114:117]
	v_mfma_f32_16x16x32_bf16 v[50:53], v[154:157], v[194:197], v[50:53]
	v_mfma_f32_16x16x32_bf16 v[106:109], v[142:145], v[218:221], v[106:109]
	v_mfma_f32_16x16x32_bf16 v[42:45], v[154:157], v[218:221], v[42:45]
	v_mfma_f32_16x16x32_bf16 v[98:101], v[142:145], v[226:229], v[98:101]
	v_mfma_f32_16x16x32_bf16 v[34:37], v[154:157], v[226:229], v[34:37]
	v_mfma_f32_16x16x32_bf16 v[146:149], v[150:153], v[190:193], v[146:149]
	v_mfma_f32_16x16x32_bf16 v[58:61], v[158:161], v[190:193], v[58:61]
	v_mfma_f32_16x16x32_bf16 v[114:117], v[150:153], v[198:201], v[114:117]
	v_mfma_f32_16x16x32_bf16 v[50:53], v[158:161], v[198:201], v[50:53]
	v_mfma_f32_16x16x32_bf16 v[106:109], v[150:153], v[222:225], v[106:109]
	v_mfma_f32_16x16x32_bf16 v[42:45], v[158:161], v[222:225], v[42:45]
	v_mfma_f32_16x16x32_bf16 v[98:101], v[150:153], v[230:233], v[98:101]
	v_mfma_f32_16x16x32_bf16 v[34:37], v[158:161], v[230:233], v[34:37]
	s_setprio 0
	s_barrier
	s_add_i32 s30, s40, s76
	s_mov_b32 m0, s30
	s_add_u32 vcc_lo, s26, s4
	s_addc_u32 vcc_hi, s27, s5
	ds_read_b128 v[172:175], v188 offset:49152
	ds_read_b128 v[190:193], v188 offset:50176
	ds_read_b128 v[194:197], v188 offset:51200
	ds_read_b128 v[198:201], v188 offset:52224
	ds_read_b128 v[218:221], v188 offset:53248
	ds_read_b128 v[222:225], v188 offset:54272
	ds_read_b128 v[226:229], v188 offset:55296
	ds_read_b128 v[230:233], v188 offset:56320
	global_load_lds_dwordx4 v0, vcc
	s_add_i32 m0, s30, 0x2000
	s_add_u32 s26, s26, 0x40080
	s_addc_u32 s27, s27, 0
	s_add_i32 s30, s41, s76
	global_load_lds_dwordx4 v166, vcc
	s_mov_b32 m0, s30
	s_nop 0
	global_load_lds_dwordx4 v0, s[26:27]
	s_add_i32 m0, s30, 0x2000
	s_nop 0
	global_load_lds_dwordx4 v166, s[26:27]
	s_mov_b32 m0, s87
	s_nop 0
	global_load_lds_dwordx4 v162, s[100:101]
	s_mov_b32 m0, s92
	s_nop 0
	global_load_lds_dwordx4 v164, s[100:101]
	s_waitcnt vmcnt(8)
	s_waitcnt lgkmcnt(0)
	s_barrier
	s_setprio 1
	s_waitcnt lgkmcnt(0)
	v_mfma_f32_16x16x32_bf16 v[94:97], v[122:125], v[172:175], v[94:97]
	v_mfma_f32_16x16x32_bf16 v[30:33], v[134:137], v[172:175], v[30:33]
	v_mfma_f32_16x16x32_bf16 v[86:89], v[122:125], v[194:197], v[86:89]
	v_mfma_f32_16x16x32_bf16 v[22:25], v[134:137], v[194:197], v[22:25]
	v_mfma_f32_16x16x32_bf16 v[78:81], v[122:125], v[218:221], v[78:81]
	v_mfma_f32_16x16x32_bf16 v[14:17], v[134:137], v[218:221], v[14:17]
	v_mfma_f32_16x16x32_bf16 v[70:73], v[122:125], v[226:229], v[70:73]
	v_mfma_f32_16x16x32_bf16 v[6:9], v[134:137], v[226:229], v[6:9]
	v_mfma_f32_16x16x32_bf16 v[94:97], v[130:133], v[190:193], v[94:97]
	v_mfma_f32_16x16x32_bf16 v[30:33], v[138:141], v[190:193], v[30:33]
	v_mfma_f32_16x16x32_bf16 v[86:89], v[130:133], v[198:201], v[86:89]
	v_mfma_f32_16x16x32_bf16 v[22:25], v[138:141], v[198:201], v[22:25]
	v_mfma_f32_16x16x32_bf16 v[78:81], v[130:133], v[222:225], v[78:81]
	v_mfma_f32_16x16x32_bf16 v[14:17], v[138:141], v[222:225], v[14:17]
	v_mfma_f32_16x16x32_bf16 v[70:73], v[130:133], v[230:233], v[70:73]
	v_mfma_f32_16x16x32_bf16 v[6:9], v[138:141], v[230:233], v[6:9]
	s_setprio 0
	s_setprio 1
	v_mfma_f32_16x16x32_bf16 v[90:93], v[142:145], v[172:175], v[90:93]
	v_mfma_f32_16x16x32_bf16 v[26:29], v[154:157], v[172:175], v[26:29]
	v_mfma_f32_16x16x32_bf16 v[82:85], v[142:145], v[194:197], v[82:85]
	v_mfma_f32_16x16x32_bf16 v[18:21], v[154:157], v[194:197], v[18:21]
	v_mfma_f32_16x16x32_bf16 v[74:77], v[142:145], v[218:221], v[74:77]
	v_mfma_f32_16x16x32_bf16 v[10:13], v[154:157], v[218:221], v[10:13]
	v_mfma_f32_16x16x32_bf16 v[66:69], v[142:145], v[226:229], v[66:69]
	v_mfma_f32_16x16x32_bf16 v[2:5], v[154:157], v[226:229], v[2:5]
	v_mfma_f32_16x16x32_bf16 v[90:93], v[150:153], v[190:193], v[90:93]
	v_mfma_f32_16x16x32_bf16 v[26:29], v[158:161], v[190:193], v[26:29]
	v_mfma_f32_16x16x32_bf16 v[82:85], v[150:153], v[198:201], v[82:85]
	v_mfma_f32_16x16x32_bf16 v[18:21], v[158:161], v[198:201], v[18:21]
	v_mfma_f32_16x16x32_bf16 v[74:77], v[150:153], v[222:225], v[74:77]
	v_mfma_f32_16x16x32_bf16 v[10:13], v[158:161], v[222:225], v[10:13]
	v_mfma_f32_16x16x32_bf16 v[66:69], v[150:153], v[230:233], v[66:69]
	v_mfma_f32_16x16x32_bf16 v[2:5], v[158:161], v[230:233], v[2:5]
	s_setprio 0
	s_barrier
	s_add_i32 s35, s35, 2
	s_add_u32 s0, s0, 0x100
	s_addc_u32 s1, s1, 0
	s_add_u32 s33, s33, 0x100
	s_addc_u32 s34, s34, 0
	s_cmp_gt_u32 s35, 13
	s_cbranch_scc0 .LBB0_70
	s_and_b64 vcc, exec, s[62:63]
	s_cbranch_vccz .LBB0_73
	s_barrier

.Lmods_nopf:
	s_add_i32 s22, s22, 16
	ds_read_b128 v[54:57], v38 offset:0
	ds_read_b128 v[58:61], v38 offset:2048
	ds_read_b128 v[62:65], v38 offset:4096
	ds_read_b128 v[66:69], v38 offset:6144
	ds_read_b128 v[70:73], v38 offset:8192
	ds_read_b128 v[74:77], v38 offset:10240
	ds_read_b128 v[78:81], v38 offset:12288
	ds_read_b128 v[82:85], v38 offset:14336
	ds_read_b128 v[86:89], v38 offset:16384
	ds_read_b128 v[136:139], v38 offset:16
	ds_read_b128 v[140:143], v38 offset:2064
	ds_read_b128 v[144:147], v38 offset:4112
	ds_read_b128 v[148:151], v38 offset:6160
	ds_read_b128 v[152:155], v38 offset:8208
	ds_read_b128 v[156:159], v38 offset:10256
	ds_read_b128 v[160:163], v38 offset:12304
	ds_read_b128 v[164:167], v38 offset:14352
	ds_read_b128 v[168:171], v38 offset:16400
	s_waitcnt lgkmcnt(9)
	v_mul_f32_e32 v90, v121, v55
	v_mul_f32_e32 v91, v123, v57
	v_fmac_f32_e32 v90, v120, v54
	v_fmac_f32_e32 v91, v122, v56
	v_add_f32_e32 v90, v90, v91
	v_add_f32_e32 v22, v22, v90
	v_mul_f32_e32 v90, v121, v59
	v_mul_f32_e32 v91, v123, v61
	v_fmac_f32_e32 v90, v120, v58
	v_fmac_f32_e32 v91, v122, v60
	v_add_f32_e32 v90, v90, v91
	v_add_f32_e32 v23, v23, v90
	v_mul_f32_e32 v90, v121, v63
	v_mul_f32_e32 v91, v123, v65
	v_fmac_f32_e32 v90, v120, v62
	v_fmac_f32_e32 v91, v122, v64
	v_add_f32_e32 v90, v90, v91
	v_add_f32_e32 v24, v24, v90
	v_mul_f32_e32 v90, v121, v67
	v_mul_f32_e32 v91, v123, v69
	v_fmac_f32_e32 v90, v120, v66
	v_fmac_f32_e32 v91, v122, v68
	v_add_f32_e32 v90, v90, v91
	v_add_f32_e32 v25, v25, v90
	v_mul_f32_e32 v90, v121, v71
	v_mul_f32_e32 v91, v123, v73
	v_fmac_f32_e32 v90, v120, v70
	v_fmac_f32_e32 v91, v122, v72
	v_add_f32_e32 v90, v90, v91
	v_add_f32_e32 v26, v26, v90
	v_mul_f32_e32 v90, v121, v75
	v_mul_f32_e32 v91, v123, v77
	v_fmac_f32_e32 v90, v120, v74
	v_fmac_f32_e32 v91, v122, v76
	v_add_f32_e32 v90, v90, v91
	v_add_f32_e32 v27, v27, v90
	v_mul_f32_e32 v90, v121, v79
	v_mul_f32_e32 v91, v123, v81
	v_fmac_f32_e32 v90, v120, v78
	v_fmac_f32_e32 v91, v122, v80
	v_add_f32_e32 v90, v90, v91
	v_add_f32_e32 v28, v28, v90
	v_mul_f32_e32 v90, v121, v83
	v_mul_f32_e32 v91, v123, v85
	v_fmac_f32_e32 v90, v120, v82
	v_fmac_f32_e32 v91, v122, v84
	v_add_f32_e32 v90, v90, v91
	v_add_f32_e32 v29, v29, v90
	v_mul_f32_e32 v90, v121, v87
	v_mul_f32_e32 v91, v123, v89
	v_fmac_f32_e32 v90, v120, v86
	v_fmac_f32_e32 v91, v122, v88
	v_add_f32_e32 v90, v90, v91
	v_add_f32_e32 v0, v0, v90
	ds_read_b128 v[54:57], v38 offset:32
	ds_read_b128 v[58:61], v38 offset:2080
	ds_read_b128 v[62:65], v38 offset:4128
	ds_read_b128 v[66:69], v38 offset:6176
	ds_read_b128 v[70:73], v38 offset:8224
	ds_read_b128 v[74:77], v38 offset:10272
	ds_read_b128 v[78:81], v38 offset:12320
	ds_read_b128 v[82:85], v38 offset:14368
	ds_read_b128 v[86:89], v38 offset:16416
	s_waitcnt lgkmcnt(9)
	v_mul_f32_e32 v90, v125, v137
	v_mul_f32_e32 v91, v127, v139
	v_fmac_f32_e32 v90, v124, v136
	v_fmac_f32_e32 v91, v126, v138
	v_add_f32_e32 v90, v90, v91
	v_add_f32_e32 v22, v22, v90
	v_mul_f32_e32 v90, v125, v141
	v_mul_f32_e32 v91, v127, v143
	v_fmac_f32_e32 v90, v124, v140
	v_fmac_f32_e32 v91, v126, v142
	v_add_f32_e32 v90, v90, v91
	v_add_f32_e32 v23, v23, v90
	v_mul_f32_e32 v90, v125, v145
	v_mul_f32_e32 v91, v127, v147
	v_fmac_f32_e32 v90, v124, v144
	v_fmac_f32_e32 v91, v126, v146
	v_add_f32_e32 v90, v90, v91
	v_add_f32_e32 v24, v24, v90
	v_mul_f32_e32 v90, v125, v149
	v_mul_f32_e32 v91, v127, v151
	v_fmac_f32_e32 v90, v124, v148
	v_fmac_f32_e32 v91, v126, v150
	v_add_f32_e32 v90, v90, v91
	v_add_f32_e32 v25, v25, v90
	v_mul_f32_e32 v90, v125, v153
	v_mul_f32_e32 v91, v127, v155
	v_fmac_f32_e32 v90, v124, v152
	v_fmac_f32_e32 v91, v126, v154
	v_add_f32_e32 v90, v90, v91
	v_add_f32_e32 v26, v26, v90
	v_mul_f32_e32 v90, v125, v157
	v_mul_f32_e32 v91, v127, v159
	v_fmac_f32_e32 v90, v124, v156
	v_fmac_f32_e32 v91, v126, v158
	v_add_f32_e32 v90, v90, v91
	v_add_f32_e32 v27, v27, v90
	v_mul_f32_e32 v90, v125, v161
	v_mul_f32_e32 v91, v127, v163
	v_fmac_f32_e32 v90, v124, v160
	v_fmac_f32_e32 v91, v126, v162
	v_add_f32_e32 v90, v90, v91
	v_add_f32_e32 v28, v28, v90
	v_mul_f32_e32 v90, v125, v165
	v_mul_f32_e32 v91, v127, v167
	v_fmac_f32_e32 v90, v124, v164
	v_fmac_f32_e32 v91, v126, v166
	v_add_f32_e32 v90, v90, v91
	v_add_f32_e32 v29, v29, v90
	v_mul_f32_e32 v90, v125, v169
	v_mul_f32_e32 v91, v127, v171
	v_fmac_f32_e32 v90, v124, v168
	v_fmac_f32_e32 v91, v126, v170
	v_add_f32_e32 v90, v90, v91
	v_add_f32_e32 v0, v0, v90
	ds_read_b128 v[136:139], v38 offset:48
	ds_read_b128 v[140:143], v38 offset:2096
	ds_read_b128 v[144:147], v38 offset:4144
	ds_read_b128 v[148:151], v38 offset:6192
	ds_read_b128 v[152:155], v38 offset:8240
	ds_read_b128 v[156:159], v38 offset:10288
	ds_read_b128 v[160:163], v38 offset:12336
	ds_read_b128 v[164:167], v38 offset:14384
	ds_read_b128 v[168:171], v38 offset:16432
	s_waitcnt lgkmcnt(9)
	v_mul_f32_e32 v90, v129, v55
	v_mul_f32_e32 v91, v131, v57
	v_fmac_f32_e32 v90, v128, v54
	v_fmac_f32_e32 v91, v130, v56
	v_add_f32_e32 v90, v90, v91
	v_add_f32_e32 v22, v22, v90
	v_mul_f32_e32 v90, v129, v59
	v_mul_f32_e32 v91, v131, v61
	v_fmac_f32_e32 v90, v128, v58
	v_fmac_f32_e32 v91, v130, v60
	v_add_f32_e32 v90, v90, v91
	v_add_f32_e32 v23, v23, v90
	v_mul_f32_e32 v90, v129, v63
	v_mul_f32_e32 v91, v131, v65
	v_fmac_f32_e32 v90, v128, v62
	v_fmac_f32_e32 v91, v130, v64
	v_add_f32_e32 v90, v90, v91
	v_add_f32_e32 v24, v24, v90
	v_mul_f32_e32 v90, v129, v67
	v_mul_f32_e32 v91, v131, v69
	v_fmac_f32_e32 v90, v128, v66
	v_fmac_f32_e32 v91, v130, v68
	v_add_f32_e32 v90, v90, v91
	v_add_f32_e32 v25, v25, v90
	v_mul_f32_e32 v90, v129, v71
	v_mul_f32_e32 v91, v131, v73
	v_fmac_f32_e32 v90, v128, v70
	v_fmac_f32_e32 v91, v130, v72
	v_add_f32_e32 v90, v90, v91
	v_add_f32_e32 v26, v26, v90
	v_mul_f32_e32 v90, v129, v75
	v_mul_f32_e32 v91, v131, v77
	v_fmac_f32_e32 v90, v128, v74
	v_fmac_f32_e32 v91, v130, v76
	v_add_f32_e32 v90, v90, v91
	v_add_f32_e32 v27, v27, v90
	v_mul_f32_e32 v90, v129, v79
	v_mul_f32_e32 v91, v131, v81
	v_fmac_f32_e32 v90, v128, v78
	v_fmac_f32_e32 v91, v130, v80
	v_add_f32_e32 v90, v90, v91
	v_add_f32_e32 v28, v28, v90
	v_mul_f32_e32 v90, v129, v83
	v_mul_f32_e32 v91, v131, v85
	v_fmac_f32_e32 v90, v128, v82
	v_fmac_f32_e32 v91, v130, v84
	v_add_f32_e32 v90, v90, v91
	v_add_f32_e32 v29, v29, v90
	v_mul_f32_e32 v90, v129, v87
	v_mul_f32_e32 v91, v131, v89
	v_fmac_f32_e32 v90, v128, v86
	v_fmac_f32_e32 v91, v130, v88
	v_add_f32_e32 v90, v90, v91
	v_add_f32_e32 v0, v0, v90
	s_waitcnt lgkmcnt(0)
	v_mul_f32_e32 v90, v133, v137
	v_mul_f32_e32 v91, v135, v139
	v_fmac_f32_e32 v90, v132, v136
	v_fmac_f32_e32 v91, v134, v138
	v_add_f32_e32 v90, v90, v91
	v_add_f32_e32 v22, v22, v90
	v_mul_f32_e32 v90, v133, v141
	v_mul_f32_e32 v91, v135, v143
	v_fmac_f32_e32 v90, v132, v140
	v_fmac_f32_e32 v91, v134, v142
	v_add_f32_e32 v90, v90, v91
	v_add_f32_e32 v23, v23, v90
	v_mul_f32_e32 v90, v133, v145
	v_mul_f32_e32 v91, v135, v147
	v_fmac_f32_e32 v90, v132, v144
	v_fmac_f32_e32 v91, v134, v146
	v_add_f32_e32 v90, v90, v91
	v_add_f32_e32 v24, v24, v90
	v_mul_f32_e32 v90, v133, v149
	v_mul_f32_e32 v91, v135, v151
	v_fmac_f32_e32 v90, v132, v148
	v_fmac_f32_e32 v91, v134, v150
	v_add_f32_e32 v90, v90, v91
	v_add_f32_e32 v25, v25, v90
	v_mul_f32_e32 v90, v133, v153
	v_mul_f32_e32 v91, v135, v155
	v_fmac_f32_e32 v90, v132, v152
	v_fmac_f32_e32 v91, v134, v154
	v_add_f32_e32 v90, v90, v91
	v_add_f32_e32 v26, v26, v90
	v_mul_f32_e32 v90, v133, v157
	v_mul_f32_e32 v91, v135, v159
	v_fmac_f32_e32 v90, v132, v156
	v_fmac_f32_e32 v91, v134, v158
	v_add_f32_e32 v90, v90, v91
	v_add_f32_e32 v27, v27, v90
	v_mul_f32_e32 v90, v133, v161
	v_mul_f32_e32 v91, v135, v163
	v_fmac_f32_e32 v90, v132, v160
	v_fmac_f32_e32 v91, v134, v162
	v_add_f32_e32 v90, v90, v91
	v_add_f32_e32 v28, v28, v90
	v_mul_f32_e32 v90, v133, v165
	v_mul_f32_e32 v91, v135, v167
	v_fmac_f32_e32 v90, v132, v164
	v_fmac_f32_e32 v91, v134, v166
	v_add_f32_e32 v90, v90, v91
	v_add_f32_e32 v29, v29, v90
	v_mul_f32_e32 v90, v133, v169
	v_mul_f32_e32 v91, v135, v171
	v_fmac_f32_e32 v90, v132, v168
	v_fmac_f32_e32 v91, v134, v170
	v_add_f32_e32 v90, v90, v91
	v_add_f32_e32 v0, v0, v90
	v_add_u32_e32 v38, 64, v38
	s_mov_b64 s[26:27], 0xc0000
	v_lshl_add_u64 v[20:21], v[20:21], 0, s[26:27]
	s_cmp_gt_u32 s22, 59
	s_cbranch_scc0 .LBB0_1022
	v_add_u32_e32 v2, 0xa000, v37
	ds_write2_b32 v2, v22, v23 offset1:32
	ds_write2_b32 v2, v24, v25 offset0:64 offset1:96
	ds_write2_b32 v2, v26, v27 offset0:128 offset1:160
	ds_write2_b32 v2, v28, v29 offset0:192 offset1:224
	ds_write_b32 v37, v0 offset:41984
	s_waitcnt lgkmcnt(0)
	s_barrier
	s_and_saveexec_b64 s[22:23], s[38:39]
	s_cbranch_execz .LBB0_1020
	s_mul_i32 s25, s24, 0x1800
	s_add_i32 s26, s25, s0
	v_or_b32_e32 v2, s26, v14
	v_readlane_b32 s56, v253, 6
	v_ashrrev_i32_e32 v3, 31, v2
	v_readlane_b32 s58, v253, 8
	v_readlane_b32 s59, v253, 9
	v_readlane_b32 s64, v253, 14
	v_readlane_b32 s65, v253, 15
	s_mul_hi_i32 s25, s24, 9
	s_mul_i32 s24, s24, 9
	v_readlane_b32 s64, v253, 49
	v_lshl_add_u64 v[2:3], v[2:3], 2, s[58:59]
	v_lshl_add_u64 v[4:5], s[0:1], 2, v[16:17]
	s_mov_b64 s[0:1], 0
	v_mov_b32_e32 v0, v184
	v_readlane_b32 s57, v253, 7
	v_readlane_b32 s60, v253, 10
	v_readlane_b32 s61, v253, 11
	v_readlane_b32 s62, v253, 12
	v_readlane_b32 s63, v253, 13
	v_readlane_b32 s66, v253, 16
	v_readlane_b32 s67, v253, 17
	v_readlane_b32 s68, v253, 18
	v_readlane_b32 s69, v253, 19
	v_readlane_b32 s70, v253, 20
	v_readlane_b32 s71, v253, 21
	v_readlane_b32 s65, v253, 50
